# ConvFused gate epilogue: 16 warm-up loads of the unit's own Z rows at epilogue start (Z lines are out of L2 by then) so the 8 dependent load batches hit L2
# baseline (speedup 1.0000x reference)
.LBB0_165:
	v_lshl_add_u32 v202, s75, 8, v225
	v_lshlrev_b32_e32 v231, 1, v202
	v_lshlrev_b32_e32 v199, 11, v198
	v_mov_b32_e32 v203, v177
	v_add_u32_e32 v176, v199, v231
	global_load_dwordx4 v[244:247], v176, s[30:31]
	global_load_dwordx4 v[244:247], v176, s[30:31] offset:256
	v_add_u32_e32 v248, 0x8000, v176
	global_load_dwordx4 v[244:247], v248, s[30:31]
	global_load_dwordx4 v[244:247], v248, s[30:31] offset:256
	v_add_u32_e32 v248, 0x10000, v176
	global_load_dwordx4 v[244:247], v248, s[30:31]
	global_load_dwordx4 v[244:247], v248, s[30:31] offset:256
	v_add_u32_e32 v248, 0x18000, v176
	global_load_dwordx4 v[244:247], v248, s[30:31]
	global_load_dwordx4 v[244:247], v248, s[30:31] offset:256
	v_add_u32_e32 v248, 0x40000, v176
	global_load_dwordx4 v[244:247], v248, s[30:31]
	global_load_dwordx4 v[244:247], v248, s[30:31] offset:256
	v_add_u32_e32 v248, 0x48000, v176
	global_load_dwordx4 v[244:247], v248, s[30:31]
	global_load_dwordx4 v[244:247], v248, s[30:31] offset:256
	v_add_u32_e32 v248, 0x50000, v176
	global_load_dwordx4 v[244:247], v248, s[30:31]
	global_load_dwordx4 v[244:247], v248, s[30:31] offset:256
	v_add_u32_e32 v248, 0x58000, v176
	global_load_dwordx4 v[244:247], v248, s[30:31]
	global_load_dwordx4 v[244:247], v248, s[30:31] offset:256
	v_and_b32_e32 v205, 0xce, v198
	v_lshlrev_b64 v[136:137], 2, v[202:203]
	v_add_u32_e32 v152, 0xfffff800, v176
	v_cmp_eq_u32_e64 s[44:45], 0, v205
	v_add_u32_e32 v153, 0xfffff000, v176
	v_or_b32_e32 v203, 0x8000, v199
	v_lshl_add_u64 v[200:201], s[22:23], 0, v[136:137]
	v_lshl_add_u64 v[138:139], s[20:21], 0, v[136:137]
	v_lshl_add_u64 v[148:149], s[18:19], 0, v[136:137]
	v_cndmask_b32_e64 v152, v152, v176, s[44:45]
	v_cndmask_b32_e64 v153, v153, v176, s[44:45]
	v_add_u32_e32 v206, v203, v231
	s_waitcnt lgkmcnt(0)
	global_load_dwordx4 v[128:131], v[200:201], off offset:16
	global_load_dwordx4 v[140:143], v[200:201], off
	global_load_dwordx4 v[132:135], v[138:139], off offset:16
	global_load_dwordx4 v[144:147], v[138:139], off
	s_nop 0
	global_load_dwordx4 v[136:139], v[148:149], off offset:16
	s_nop 0
	global_load_dwordx4 v[148:151], v[148:149], off
	s_nop 0
	global_load_dwordx4 v[168:171], v152, s[30:31]
	global_load_dwordx4 v[164:167], v153, s[30:31]
	v_add_u32_e32 v152, 0xfffff800, v206
	v_add_u32_e32 v153, 0xfffff000, v206
	global_load_dwordx4 v[172:175], v176, s[30:31]
	global_load_dwordx4 v[160:163], v206, s[30:31]
	global_load_dwordx4 v[156:159], v152, s[30:31]
	s_nop 0
	global_load_dwordx4 v[152:155], v153, s[30:31]
	ds_read_b32 v204, v227
	v_cmp_ne_u32_e32 vcc, 0, v205
	v_mov_b64_e32 v[216:217], 0xe900000
	s_waitcnt lgkmcnt(0)
	v_pk_mul_f32 v[212:213], v[122:123], v[204:205] op_sel_hi:[1,0]
	v_pk_mul_f32 v[214:215], v[120:121], v[204:205] op_sel_hi:[1,0]
	v_pk_mul_f32 v[208:209], v[118:119], v[204:205] op_sel_hi:[1,0]
	v_pk_mul_f32 v[210:211], v[116:117], v[204:205] op_sel_hi:[1,0]
	v_mov_b64_e32 v[204:205], 0xe900000
	s_and_saveexec_b64 s[42:43], vcc
	s_cbranch_execz .LBB0_167
	s_waitcnt vmcnt(0)
	v_lshlrev_b32_e32 v238, 16, v164
	v_and_b32_e32 v239, 0xffff0000, v164
	v_lshlrev_b32_e32 v164, 16, v165
	v_and_b32_e32 v165, 0xffff0000, v165
	v_lshlrev_b32_e32 v234, 16, v168
	v_and_b32_e32 v235, 0xffff0000, v168
	v_lshlrev_b32_e32 v168, 16, v169
	v_and_b32_e32 v169, 0xffff0000, v169
	v_pk_mul_f32 v[164:165], v[142:143], v[164:165]
	v_lshlrev_b32_e32 v216, 16, v172
	v_and_b32_e32 v217, 0xffff0000, v172
	v_lshlrev_b32_e32 v172, 16, v173
	v_and_b32_e32 v173, 0xffff0000, v173
	v_pk_fma_f32 v[164:165], v[146:147], v[168:169], v[164:165]
	v_lshlrev_b32_e32 v240, 16, v166
	v_and_b32_e32 v241, 0xffff0000, v166
	v_lshlrev_b32_e32 v166, 16, v167
	v_and_b32_e32 v167, 0xffff0000, v167
	v_pk_fma_f32 v[164:165], v[150:151], v[172:173], v[164:165]
	v_lshlrev_b32_e32 v236, 16, v170
	v_and_b32_e32 v237, 0xffff0000, v170
	v_lshlrev_b32_e32 v170, 16, v171
	v_and_b32_e32 v171, 0xffff0000, v171
	v_pk_mul_f32 v[238:239], v[140:141], v[238:239]
	v_pk_mul_f32 v[212:213], v[212:213], v[164:165]
	v_pk_mul_f32 v[164:165], v[128:129], v[240:241]
	v_pk_mul_f32 v[166:167], v[130:131], v[166:167]
	v_lshlrev_b32_e32 v232, 16, v174
	v_and_b32_e32 v233, 0xffff0000, v174
	v_lshlrev_b32_e32 v174, 16, v175
	v_and_b32_e32 v175, 0xffff0000, v175
	v_pk_fma_f32 v[168:169], v[144:145], v[234:235], v[238:239]
	v_pk_fma_f32 v[166:167], v[134:135], v[170:171], v[166:167]
	v_pk_fma_f32 v[164:165], v[132:133], v[236:237], v[164:165]
	v_pk_fma_f32 v[168:169], v[148:149], v[216:217], v[168:169]
	v_pk_fma_f32 v[164:165], v[136:137], v[232:233], v[164:165]
	v_pk_fma_f32 v[166:167], v[138:139], v[174:175], v[166:167]
	v_pk_mul_f32 v[214:215], v[214:215], v[168:169]
	v_pk_mul_f32 v[208:209], v[208:209], v[166:167]
	v_pk_mul_f32 v[210:211], v[210:211], v[164:165]
	v_mov_b64_e32 v[216:217], 0x12d00000
	s_and_b32 s98, s2, 7
	s_mul_i32 s98, s98, 0xe00000
	v_add_u32_e32 v216, s98, v216
